# prep: unroll the 13 transpose staging inner loops (8 row loads in flight instead of load-wait-write x8)
# speedup vs baseline: 1.0170x; 1.0111x over previous
; DI void prep_transpose(const float* W, int K, int Nsrc, int Nd, int kind, const float* kscale, bf16_t* dst, float* tileL, int L, int G) {
;     ...
;     const int tx = tid & 63, ty = tid >> 6;
;     const int src = colmap(kind, n0 + tx);
;     __syncthreads();
;     for (int kk = ty; kk < 64; kk += 8) {
;       float v = 0.f;
;       if (src >= 0) { v = W[(size_t)(k0 + kk) * Nsrc + src]; if (kscale) v *= kscale[k0 + kk]; }
;       tileL[kk * 65 + tx] = v;
;     }
.LBB0_28:
	v_mov_b32_e32 v40, 0
	v_mov_b32_e32 v56, 0
	v_mov_b32_e32 v72, 0
	v_mov_b32_e32 v88, 0
	v_mov_b32_e32 v104, 0
	v_mov_b32_e32 v120, 0
	v_mov_b32_e32 v136, 0
	v_mov_b32_e32 v152, 0
	s_and_b64 vcc, exec, s[2:3]
	s_cbranch_vccnz .Lmy_tp0_w
	v_add_u32_e32 v40, s33, v13
	v_mad_i64_i32 v[40:41], s[34:35], v40, s28, v[6:7]
	global_load_dword v40, v[40:41], off
	v_add_u32_e32 v71, 8, v13
	v_add_u32_e32 v56, s33, v71
	v_mad_i64_i32 v[56:57], s[34:35], v56, s28, v[6:7]
	global_load_dword v56, v[56:57], off
	v_add_u32_e32 v87, 16, v13
	v_add_u32_e32 v72, s33, v87
	v_mad_i64_i32 v[72:73], s[34:35], v72, s28, v[6:7]
	global_load_dword v72, v[72:73], off
	v_add_u32_e32 v103, 24, v13
	v_add_u32_e32 v88, s33, v103
	v_mad_i64_i32 v[88:89], s[34:35], v88, s28, v[6:7]
	global_load_dword v88, v[88:89], off
	v_add_u32_e32 v119, 32, v13
	v_add_u32_e32 v104, s33, v119
	v_mad_i64_i32 v[104:105], s[34:35], v104, s28, v[6:7]
	global_load_dword v104, v[104:105], off
	v_add_u32_e32 v135, 40, v13
	v_add_u32_e32 v120, s33, v135
	v_mad_i64_i32 v[120:121], s[34:35], v120, s28, v[6:7]
	global_load_dword v120, v[120:121], off
	v_add_u32_e32 v151, 48, v13
	v_add_u32_e32 v136, s33, v151
	v_mad_i64_i32 v[136:137], s[34:35], v136, s28, v[6:7]
	global_load_dword v136, v[136:137], off
	v_add_u32_e32 v167, 56, v13
	v_add_u32_e32 v152, s33, v167
	v_mad_i64_i32 v[152:153], s[34:35], v152, s28, v[6:7]
	global_load_dword v152, v[152:153], off
.Lmy_tp0_r:
.Lmy_tp0_w:
	s_waitcnt vmcnt(7)
	ds_write_b32 v2, v40
	s_waitcnt vmcnt(6)
	ds_write_b32 v2, v56 offset:2080
	s_waitcnt vmcnt(5)
	ds_write_b32 v2, v72 offset:4160
	s_waitcnt vmcnt(4)
	ds_write_b32 v2, v88 offset:6240
	s_waitcnt vmcnt(3)
	ds_write_b32 v2, v104 offset:8320
	s_waitcnt vmcnt(2)
	ds_write_b32 v2, v120 offset:10400
	s_waitcnt vmcnt(1)
	ds_write_b32 v2, v136 offset:12480
	s_waitcnt vmcnt(0)
	ds_write_b32 v2, v152 offset:14560
	s_branch .LBB0_24

; DI void prep_transpose(const float* W, int K, int Nsrc, int Nd, int kind, const float* kscale, bf16_t* dst, float* tileL, int L, int G) {
;     ...
;     const int tx = tid & 63, ty = tid >> 6;
;     const int src = colmap(kind, n0 + tx);
;     __syncthreads();
;     for (int kk = ty; kk < 64; kk += 8) {
;       float v = 0.f;
;       if (src >= 0) { v = W[(size_t)(k0 + kk) * Nsrc + src]; if (kscale) v *= kscale[k0 + kk]; }
;       tileL[kk * 65 + tx] = v;
;     }
.LBB0_42:
	v_mov_b32_e32 v40, 0
	v_mov_b32_e32 v56, 0
	v_mov_b32_e32 v72, 0
	v_mov_b32_e32 v88, 0
	v_mov_b32_e32 v104, 0
	v_mov_b32_e32 v120, 0
	v_mov_b32_e32 v136, 0
	v_mov_b32_e32 v152, 0
	s_and_saveexec_b64 s[2:3], vcc
	s_cbranch_execz .Lmy_tp1_r
	v_add_u32_e32 v40, s35, v13
	v_mad_i64_i32 v[40:41], s[36:37], v40, s30, v[6:7]
	global_load_dword v40, v[40:41], off
	v_add_u32_e32 v71, 8, v13
	v_add_u32_e32 v56, s35, v71
	v_mad_i64_i32 v[56:57], s[36:37], v56, s30, v[6:7]
	global_load_dword v56, v[56:57], off
	v_add_u32_e32 v87, 16, v13
	v_add_u32_e32 v72, s35, v87
	v_mad_i64_i32 v[72:73], s[36:37], v72, s30, v[6:7]
	global_load_dword v72, v[72:73], off
	v_add_u32_e32 v103, 24, v13
	v_add_u32_e32 v88, s35, v103
	v_mad_i64_i32 v[88:89], s[36:37], v88, s30, v[6:7]
	global_load_dword v88, v[88:89], off
	v_add_u32_e32 v119, 32, v13
	v_add_u32_e32 v104, s35, v119
	v_mad_i64_i32 v[104:105], s[36:37], v104, s30, v[6:7]
	global_load_dword v104, v[104:105], off
	v_add_u32_e32 v135, 40, v13
	v_add_u32_e32 v120, s35, v135
	v_mad_i64_i32 v[120:121], s[36:37], v120, s30, v[6:7]
	global_load_dword v120, v[120:121], off
	v_add_u32_e32 v151, 48, v13
	v_add_u32_e32 v136, s35, v151
	v_mad_i64_i32 v[136:137], s[36:37], v136, s30, v[6:7]
	global_load_dword v136, v[136:137], off
	v_add_u32_e32 v167, 56, v13
	v_add_u32_e32 v152, s35, v167
	v_mad_i64_i32 v[152:153], s[36:37], v152, s30, v[6:7]
	global_load_dword v152, v[152:153], off

; DI void prep_transpose(const float* W, int K, int Nsrc, int Nd, int kind, const float* kscale, bf16_t* dst, float* tileL, int L, int G) {
;     ...
;     const int tx = tid & 63, ty = tid >> 6;
;     const int src = colmap(kind, n0 + tx);
;     __syncthreads();
;     for (int kk = ty; kk < 64; kk += 8) {
;       float v = 0.f;
;       if (src >= 0) { v = W[(size_t)(k0 + kk) * Nsrc + src]; if (kscale) v *= kscale[k0 + kk]; }
;       tileL[kk * 65 + tx] = v;
;     }
.Lmy_tp1_w:
	s_waitcnt vmcnt(7)
	ds_write_b32 v2, v40
	s_waitcnt vmcnt(6)
	ds_write_b32 v2, v56 offset:2080
	s_waitcnt vmcnt(5)
	ds_write_b32 v2, v72 offset:4160
	s_waitcnt vmcnt(4)
	ds_write_b32 v2, v88 offset:6240
	s_waitcnt vmcnt(3)
	ds_write_b32 v2, v104 offset:8320
	s_waitcnt vmcnt(2)
	ds_write_b32 v2, v120 offset:10400
	s_waitcnt vmcnt(1)
	ds_write_b32 v2, v136 offset:12480
	s_waitcnt vmcnt(0)
	ds_write_b32 v2, v152 offset:14560
	s_branch .LBB0_32

; DI void prep_transpose(const float* W, int K, int Nsrc, int Nd, int kind, const float* kscale, bf16_t* dst, float* tileL, int L, int G) {
;     ...
;     const int tx = tid & 63, ty = tid >> 6;
;     const int src = colmap(kind, n0 + tx);
;     __syncthreads();
;     for (int kk = ty; kk < 64; kk += 8) {
;       float v = 0.f;
;       if (src >= 0) { v = W[(size_t)(k0 + kk) * Nsrc + src]; if (kscale) v *= kscale[k0 + kk]; }
;       tileL[kk * 65 + tx] = v;
;     }
.LBB0_64:
	v_mov_b32_e32 v40, 0
	v_mov_b32_e32 v56, 0
	v_mov_b32_e32 v72, 0
	v_mov_b32_e32 v88, 0
	v_mov_b32_e32 v104, 0
	v_mov_b32_e32 v120, 0
	v_mov_b32_e32 v136, 0
	v_mov_b32_e32 v152, 0
	s_and_b64 vcc, exec, s[2:3]
	s_cbranch_vccnz .Lmy_tp3_w
	v_add_u32_e32 v40, s26, v13
	v_mad_i64_i32 v[40:41], s[30:31], v40, s10, v[6:7]
	global_load_dword v40, v[40:41], off
	v_add_u32_e32 v71, 8, v13
	v_add_u32_e32 v56, s26, v71
	v_mad_i64_i32 v[56:57], s[30:31], v56, s10, v[6:7]
	global_load_dword v56, v[56:57], off
	v_add_u32_e32 v87, 16, v13
	v_add_u32_e32 v72, s26, v87
	v_mad_i64_i32 v[72:73], s[30:31], v72, s10, v[6:7]
	global_load_dword v72, v[72:73], off
	v_add_u32_e32 v103, 24, v13
	v_add_u32_e32 v88, s26, v103
	v_mad_i64_i32 v[88:89], s[30:31], v88, s10, v[6:7]
	global_load_dword v88, v[88:89], off
	v_add_u32_e32 v119, 32, v13
	v_add_u32_e32 v104, s26, v119
	v_mad_i64_i32 v[104:105], s[30:31], v104, s10, v[6:7]
	global_load_dword v104, v[104:105], off
	v_add_u32_e32 v135, 40, v13
	v_add_u32_e32 v120, s26, v135
	v_mad_i64_i32 v[120:121], s[30:31], v120, s10, v[6:7]
	global_load_dword v120, v[120:121], off
	v_add_u32_e32 v151, 48, v13
	v_add_u32_e32 v136, s26, v151
	v_mad_i64_i32 v[136:137], s[30:31], v136, s10, v[6:7]
	global_load_dword v136, v[136:137], off
	v_add_u32_e32 v167, 56, v13
	v_add_u32_e32 v152, s26, v167
	v_mad_i64_i32 v[152:153], s[30:31], v152, s10, v[6:7]
	global_load_dword v152, v[152:153], off

; DI void prep_transpose(const float* W, int K, int Nsrc, int Nd, int kind, const float* kscale, bf16_t* dst, float* tileL, int L, int G) {
;     ...
;     const int tx = tid & 63, ty = tid >> 6;
;     const int src = colmap(kind, n0 + tx);
;     __syncthreads();
;     for (int kk = ty; kk < 64; kk += 8) {
;       float v = 0.f;
;       if (src >= 0) { v = W[(size_t)(k0 + kk) * Nsrc + src]; if (kscale) v *= kscale[k0 + kk]; }
;       tileL[kk * 65 + tx] = v;
;     }
.LBB0_76:
	v_mov_b32_e32 v48, 0
	v_mov_b32_e32 v64, 0
	v_mov_b32_e32 v80, 0
	v_mov_b32_e32 v96, 0
	v_mov_b32_e32 v112, 0
	v_mov_b32_e32 v128, 0
	v_mov_b32_e32 v144, 0
	v_mov_b32_e32 v160, 0
	s_and_saveexec_b64 s[10:11], s[4:5]
	s_cbranch_execz .Lmy_tp4_r
	v_add_u32_e32 v40, s38, v17
	v_mad_i64_i32 v[48:49], s[40:41], v40, s33, v[8:9]
	global_load_dword v48, v[48:49], off
	v_add_u32_e32 v71, 8, v17
	v_add_u32_e32 v56, s38, v71
	v_mad_i64_i32 v[64:65], s[40:41], v56, s33, v[8:9]
	global_load_dword v64, v[64:65], off
	v_add_u32_e32 v87, 16, v17
	v_add_u32_e32 v72, s38, v87
	v_mad_i64_i32 v[80:81], s[40:41], v72, s33, v[8:9]
	global_load_dword v80, v[80:81], off
	v_add_u32_e32 v103, 24, v17
	v_add_u32_e32 v88, s38, v103
	v_mad_i64_i32 v[96:97], s[40:41], v88, s33, v[8:9]
	global_load_dword v96, v[96:97], off
	v_add_u32_e32 v119, 32, v17
	v_add_u32_e32 v104, s38, v119
	v_mad_i64_i32 v[112:113], s[40:41], v104, s33, v[8:9]
	global_load_dword v112, v[112:113], off
	v_add_u32_e32 v135, 40, v17
	v_add_u32_e32 v120, s38, v135
	v_mad_i64_i32 v[128:129], s[40:41], v120, s33, v[8:9]
	global_load_dword v128, v[128:129], off
	v_add_u32_e32 v151, 48, v17
	v_add_u32_e32 v136, s38, v151
	v_mad_i64_i32 v[144:145], s[40:41], v136, s33, v[8:9]
	global_load_dword v144, v[144:145], off
	v_add_u32_e32 v167, 56, v17
	v_add_u32_e32 v152, s38, v167
	v_mad_i64_i32 v[160:161], s[40:41], v152, s33, v[8:9]
	global_load_dword v160, v[160:161], off
	s_and_b64 vcc, exec, s[2:3]
	s_cbranch_vccnz .Lmy_tp4_r
	v_ashrrev_i32_e32 v41, 31, v40
	v_lshl_add_u64 v[40:41], v[40:41], 2, s[18:19]
	global_load_dword v40, v[40:41], off
	v_ashrrev_i32_e32 v57, 31, v56
	v_lshl_add_u64 v[56:57], v[56:57], 2, s[18:19]
	global_load_dword v56, v[56:57], off
	v_ashrrev_i32_e32 v73, 31, v72
	v_lshl_add_u64 v[72:73], v[72:73], 2, s[18:19]
	global_load_dword v72, v[72:73], off
	v_ashrrev_i32_e32 v89, 31, v88
	v_lshl_add_u64 v[88:89], v[88:89], 2, s[18:19]
	global_load_dword v88, v[88:89], off
	v_ashrrev_i32_e32 v105, 31, v104
	v_lshl_add_u64 v[104:105], v[104:105], 2, s[18:19]
	global_load_dword v104, v[104:105], off
	v_ashrrev_i32_e32 v121, 31, v120
	v_lshl_add_u64 v[120:121], v[120:121], 2, s[18:19]
	global_load_dword v120, v[120:121], off
	v_ashrrev_i32_e32 v137, 31, v136
	v_lshl_add_u64 v[136:137], v[136:137], 2, s[18:19]
	global_load_dword v136, v[136:137], off
	v_ashrrev_i32_e32 v153, 31, v152
	v_lshl_add_u64 v[152:153], v[152:153], 2, s[18:19]
	global_load_dword v152, v[152:153], off
	s_waitcnt vmcnt(7)
	v_mul_f32_e32 v48, v48, v40
	s_waitcnt vmcnt(6)
	v_mul_f32_e32 v64, v64, v56
	s_waitcnt vmcnt(5)
	v_mul_f32_e32 v80, v80, v72
	s_waitcnt vmcnt(4)
	v_mul_f32_e32 v96, v96, v88
	s_waitcnt vmcnt(3)
	v_mul_f32_e32 v112, v112, v104
	s_waitcnt vmcnt(2)
	v_mul_f32_e32 v128, v128, v120
	s_waitcnt vmcnt(1)
	v_mul_f32_e32 v144, v144, v136
	s_waitcnt vmcnt(0)
	v_mul_f32_e32 v160, v160, v152

; DI void prep_transpose(const float* W, int K, int Nsrc, int Nd, int kind, const float* kscale, bf16_t* dst, float* tileL, int L, int G) {
;     ...
;     const int tx = tid & 63, ty = tid >> 6;
;     const int src = colmap(kind, n0 + tx);
;     __syncthreads();
;     for (int kk = ty; kk < 64; kk += 8) {
;       float v = 0.f;
;       if (src >= 0) { v = W[(size_t)(k0 + kk) * Nsrc + src]; if (kscale) v *= kscale[k0 + kk]; }
;       tileL[kk * 65 + tx] = v;
;     }
.Lmy_tp4_w:
	s_waitcnt vmcnt(7)
	ds_write_b32 v16, v48
	s_waitcnt vmcnt(6)
	ds_write_b32 v16, v64 offset:2080
	s_waitcnt vmcnt(5)
	ds_write_b32 v16, v80 offset:4160
	s_waitcnt vmcnt(4)
	ds_write_b32 v16, v96 offset:6240
	s_waitcnt vmcnt(3)
	ds_write_b32 v16, v112 offset:8320
	s_waitcnt vmcnt(2)
	ds_write_b32 v16, v128 offset:10400
	s_waitcnt vmcnt(1)
	ds_write_b32 v16, v144 offset:12480
	s_waitcnt vmcnt(0)
	ds_write_b32 v16, v160 offset:14560
	s_branch .LBB0_68

; DI void prep_transpose(const float* W, int K, int Nsrc, int Nd, int kind, const float* kscale, bf16_t* dst, float* tileL, int L, int G) {
;     ...
;     const int tx = tid & 63, ty = tid >> 6;
;     const int src = colmap(kind, n0 + tx);
;     __syncthreads();
;     for (int kk = ty; kk < 64; kk += 8) {
;       float v = 0.f;
;       if (src >= 0) { v = W[(size_t)(k0 + kk) * Nsrc + src]; if (kscale) v *= kscale[k0 + kk]; }
;       tileL[kk * 65 + tx] = v;
;     }
.LBB0_89:
	v_mov_b32_e32 v49, 0
	v_mov_b32_e32 v65, 0
	v_mov_b32_e32 v81, 0
	v_mov_b32_e32 v97, 0
	v_mov_b32_e32 v113, 0
	v_mov_b32_e32 v129, 0
	v_mov_b32_e32 v145, 0
	v_mov_b32_e32 v161, 0
	s_and_saveexec_b64 s[12:13], s[4:5]
	s_cbranch_execz .Lmy_tp5_r
	v_add_u32_e32 v40, s37, v16
	v_ashrrev_i32_e32 v41, 31, v40
	v_lshlrev_b64 v[50:51], 13, v[40:41]
	v_lshl_add_u64 v[50:51], v[6:7], 0, v[50:51]
	global_load_dword v49, v[50:51], off
	v_add_u32_e32 v71, 8, v16
	v_add_u32_e32 v56, s37, v71
	v_ashrrev_i32_e32 v57, 31, v56
	v_lshlrev_b64 v[66:67], 13, v[56:57]
	v_lshl_add_u64 v[66:67], v[6:7], 0, v[66:67]
	global_load_dword v65, v[66:67], off
	v_add_u32_e32 v87, 16, v16
	v_add_u32_e32 v72, s37, v87
	v_ashrrev_i32_e32 v73, 31, v72
	v_lshlrev_b64 v[82:83], 13, v[72:73]
	v_lshl_add_u64 v[82:83], v[6:7], 0, v[82:83]
	global_load_dword v81, v[82:83], off
	v_add_u32_e32 v103, 24, v16
	v_add_u32_e32 v88, s37, v103
	v_ashrrev_i32_e32 v89, 31, v88
	v_lshlrev_b64 v[98:99], 13, v[88:89]
	v_lshl_add_u64 v[98:99], v[6:7], 0, v[98:99]
	global_load_dword v97, v[98:99], off
	v_add_u32_e32 v119, 32, v16
	v_add_u32_e32 v104, s37, v119
	v_ashrrev_i32_e32 v105, 31, v104
	v_lshlrev_b64 v[114:115], 13, v[104:105]
	v_lshl_add_u64 v[114:115], v[6:7], 0, v[114:115]
	global_load_dword v113, v[114:115], off
	v_add_u32_e32 v135, 40, v16
	v_add_u32_e32 v120, s37, v135
	v_ashrrev_i32_e32 v121, 31, v120
	v_lshlrev_b64 v[130:131], 13, v[120:121]
	v_lshl_add_u64 v[130:131], v[6:7], 0, v[130:131]
	global_load_dword v129, v[130:131], off
	v_add_u32_e32 v151, 48, v16
	v_add_u32_e32 v136, s37, v151
	v_ashrrev_i32_e32 v137, 31, v136
	v_lshlrev_b64 v[146:147], 13, v[136:137]
	v_lshl_add_u64 v[146:147], v[6:7], 0, v[146:147]
	global_load_dword v145, v[146:147], off
	v_add_u32_e32 v167, 56, v16
	v_add_u32_e32 v152, s37, v167
	v_ashrrev_i32_e32 v153, 31, v152
	v_lshlrev_b64 v[162:163], 13, v[152:153]
	v_lshl_add_u64 v[162:163], v[6:7], 0, v[162:163]
	global_load_dword v161, v[162:163], off
	s_and_b64 vcc, exec, s[2:3]
	s_cbranch_vccnz .Lmy_tp5_r
	v_lshl_add_u64 v[40:41], v[40:41], 2, s[20:21]
	global_load_dword v40, v[40:41], off
	v_lshl_add_u64 v[56:57], v[56:57], 2, s[20:21]
	global_load_dword v56, v[56:57], off
	v_lshl_add_u64 v[72:73], v[72:73], 2, s[20:21]
	global_load_dword v72, v[72:73], off
	v_lshl_add_u64 v[88:89], v[88:89], 2, s[20:21]
	global_load_dword v88, v[88:89], off
	v_lshl_add_u64 v[104:105], v[104:105], 2, s[20:21]
	global_load_dword v104, v[104:105], off
	v_lshl_add_u64 v[120:121], v[120:121], 2, s[20:21]
	global_load_dword v120, v[120:121], off
	v_lshl_add_u64 v[136:137], v[136:137], 2, s[20:21]
	global_load_dword v136, v[136:137], off
	v_lshl_add_u64 v[152:153], v[152:153], 2, s[20:21]
	global_load_dword v152, v[152:153], off
	s_waitcnt vmcnt(7)
	v_mul_f32_e32 v49, v49, v40
	s_waitcnt vmcnt(6)
	v_mul_f32_e32 v65, v65, v56
	s_waitcnt vmcnt(5)
	v_mul_f32_e32 v81, v81, v72
	s_waitcnt vmcnt(4)
	v_mul_f32_e32 v97, v97, v88
	s_waitcnt vmcnt(3)
	v_mul_f32_e32 v113, v113, v104
	s_waitcnt vmcnt(2)
	v_mul_f32_e32 v129, v129, v120
	s_waitcnt vmcnt(1)
	v_mul_f32_e32 v145, v145, v136
	s_waitcnt vmcnt(0)
	v_mul_f32_e32 v161, v161, v152

; DI void prep_transpose(const float* W, int K, int Nsrc, int Nd, int kind, const float* kscale, bf16_t* dst, float* tileL, int L, int G) {
;     ...
;     const int tx = tid & 63, ty = tid >> 6;
;     const int src = colmap(kind, n0 + tx);
;     __syncthreads();
;     for (int kk = ty; kk < 64; kk += 8) {
;       float v = 0.f;
;       if (src >= 0) { v = W[(size_t)(k0 + kk) * Nsrc + src]; if (kscale) v *= kscale[k0 + kk]; }
;       tileL[kk * 65 + tx] = v;
;     }
.Lmy_tp5_w:
	s_waitcnt vmcnt(7)
	ds_write_b32 v2, v49
	s_waitcnt vmcnt(6)
	ds_write_b32 v2, v65 offset:2080
	s_waitcnt vmcnt(5)
	ds_write_b32 v2, v81 offset:4160
	s_waitcnt vmcnt(4)
	ds_write_b32 v2, v97 offset:6240
	s_waitcnt vmcnt(3)
	ds_write_b32 v2, v113 offset:8320
	s_waitcnt vmcnt(2)
	ds_write_b32 v2, v129 offset:10400
	s_waitcnt vmcnt(1)
	ds_write_b32 v2, v145 offset:12480
	s_waitcnt vmcnt(0)
	ds_write_b32 v2, v161 offset:14560
	s_branch .LBB0_81

; DI void prep_transpose(const float* W, int K, int Nsrc, int Nd, int kind, const float* kscale, bf16_t* dst, float* tileL, int L, int G) {
;     ...
;     const int tx = tid & 63, ty = tid >> 6;
;     const int src = colmap(kind, n0 + tx);
;     __syncthreads();
;     for (int kk = ty; kk < 64; kk += 8) {
;       float v = 0.f;
;       if (src >= 0) { v = W[(size_t)(k0 + kk) * Nsrc + src]; if (kscale) v *= kscale[k0 + kk]; }
;       tileL[kk * 65 + tx] = v;
;     }
.LBB0_98:
	v_mov_b32_e32 v40, 0
	v_mov_b32_e32 v56, 0
	v_mov_b32_e32 v72, 0
	v_mov_b32_e32 v88, 0
	v_mov_b32_e32 v104, 0
	v_mov_b32_e32 v120, 0
	v_mov_b32_e32 v136, 0
	v_mov_b32_e32 v152, 0
	s_and_b64 vcc, exec, s[2:3]
	s_cbranch_vccnz .Lmy_tp6_w
	v_add_u32_e32 v40, s23, v13
	v_ashrrev_i32_e32 v41, 31, v40
	v_lshlrev_b64 v[40:41], 10, v[40:41]
	v_lshl_add_u64 v[40:41], v[6:7], 0, v[40:41]
	global_load_dword v40, v[40:41], off
	v_add_u32_e32 v71, 8, v13
	v_add_u32_e32 v56, s23, v71
	v_ashrrev_i32_e32 v57, 31, v56
	v_lshlrev_b64 v[56:57], 10, v[56:57]
	v_lshl_add_u64 v[56:57], v[6:7], 0, v[56:57]
	global_load_dword v56, v[56:57], off
	v_add_u32_e32 v87, 16, v13
	v_add_u32_e32 v72, s23, v87
	v_ashrrev_i32_e32 v73, 31, v72
	v_lshlrev_b64 v[72:73], 10, v[72:73]
	v_lshl_add_u64 v[72:73], v[6:7], 0, v[72:73]
	global_load_dword v72, v[72:73], off
	v_add_u32_e32 v103, 24, v13
	v_add_u32_e32 v88, s23, v103
	v_ashrrev_i32_e32 v89, 31, v88
	v_lshlrev_b64 v[88:89], 10, v[88:89]
	v_lshl_add_u64 v[88:89], v[6:7], 0, v[88:89]
	global_load_dword v88, v[88:89], off
	v_add_u32_e32 v119, 32, v13
	v_add_u32_e32 v104, s23, v119
	v_ashrrev_i32_e32 v105, 31, v104
	v_lshlrev_b64 v[104:105], 10, v[104:105]
	v_lshl_add_u64 v[104:105], v[6:7], 0, v[104:105]
	global_load_dword v104, v[104:105], off
	v_add_u32_e32 v135, 40, v13
	v_add_u32_e32 v120, s23, v135
	v_ashrrev_i32_e32 v121, 31, v120
	v_lshlrev_b64 v[120:121], 10, v[120:121]
	v_lshl_add_u64 v[120:121], v[6:7], 0, v[120:121]
	global_load_dword v120, v[120:121], off
	v_add_u32_e32 v151, 48, v13
	v_add_u32_e32 v136, s23, v151
	v_ashrrev_i32_e32 v137, 31, v136
	v_lshlrev_b64 v[136:137], 10, v[136:137]
	v_lshl_add_u64 v[136:137], v[6:7], 0, v[136:137]
	global_load_dword v136, v[136:137], off
	v_add_u32_e32 v167, 56, v13
	v_add_u32_e32 v152, s23, v167
	v_ashrrev_i32_e32 v153, 31, v152
	v_lshlrev_b64 v[152:153], 10, v[152:153]
	v_lshl_add_u64 v[152:153], v[6:7], 0, v[152:153]
	global_load_dword v152, v[152:153], off

; DI void prep_transpose(const float* W, int K, int Nsrc, int Nd, int kind, const float* kscale, bf16_t* dst, float* tileL, int L, int G) {
;     ...
;     const int tx = tid & 63, ty = tid >> 6;
;     const int src = colmap(kind, n0 + tx);
;     __syncthreads();
;     for (int kk = ty; kk < 64; kk += 8) {
;       float v = 0.f;
;       if (src >= 0) { v = W[(size_t)(k0 + kk) * Nsrc + src]; if (kscale) v *= kscale[k0 + kk]; }
;       tileL[kk * 65 + tx] = v;
;     }
.LBB0_114:
	v_mov_b32_e32 v40, 0
	v_mov_b32_e32 v56, 0
	v_mov_b32_e32 v72, 0
	v_mov_b32_e32 v88, 0
	v_mov_b32_e32 v104, 0
	v_mov_b32_e32 v120, 0
	v_mov_b32_e32 v136, 0
	v_mov_b32_e32 v152, 0
	s_and_saveexec_b64 s[2:3], s[0:1]
	s_cbranch_execz .Lmy_tp8_r
	v_add_u32_e32 v40, s25, v13
	v_ashrrev_i32_e32 v41, 31, v40
	v_lshlrev_b64 v[40:41], 8, v[40:41]
	v_lshl_add_u64 v[40:41], v[6:7], 0, v[40:41]
	global_load_dword v40, v[40:41], off
	v_add_u32_e32 v71, 8, v13
	v_add_u32_e32 v56, s25, v71
	v_ashrrev_i32_e32 v57, 31, v56
	v_lshlrev_b64 v[56:57], 8, v[56:57]
	v_lshl_add_u64 v[56:57], v[6:7], 0, v[56:57]
	global_load_dword v56, v[56:57], off
	v_add_u32_e32 v87, 16, v13
	v_add_u32_e32 v72, s25, v87
	v_ashrrev_i32_e32 v73, 31, v72
	v_lshlrev_b64 v[72:73], 8, v[72:73]
	v_lshl_add_u64 v[72:73], v[6:7], 0, v[72:73]
	global_load_dword v72, v[72:73], off
	v_add_u32_e32 v103, 24, v13
	v_add_u32_e32 v88, s25, v103
	v_ashrrev_i32_e32 v89, 31, v88
	v_lshlrev_b64 v[88:89], 8, v[88:89]
	v_lshl_add_u64 v[88:89], v[6:7], 0, v[88:89]
	global_load_dword v88, v[88:89], off
	v_add_u32_e32 v119, 32, v13
	v_add_u32_e32 v104, s25, v119
	v_ashrrev_i32_e32 v105, 31, v104
	v_lshlrev_b64 v[104:105], 8, v[104:105]
	v_lshl_add_u64 v[104:105], v[6:7], 0, v[104:105]
	global_load_dword v104, v[104:105], off
	v_add_u32_e32 v135, 40, v13
	v_add_u32_e32 v120, s25, v135
	v_ashrrev_i32_e32 v121, 31, v120
	v_lshlrev_b64 v[120:121], 8, v[120:121]
	v_lshl_add_u64 v[120:121], v[6:7], 0, v[120:121]
	global_load_dword v120, v[120:121], off
	v_add_u32_e32 v151, 48, v13
	v_add_u32_e32 v136, s25, v151
	v_ashrrev_i32_e32 v137, 31, v136
	v_lshlrev_b64 v[136:137], 8, v[136:137]
	v_lshl_add_u64 v[136:137], v[6:7], 0, v[136:137]
	global_load_dword v136, v[136:137], off
	v_add_u32_e32 v167, 56, v13
	v_add_u32_e32 v152, s25, v167
	v_ashrrev_i32_e32 v153, 31, v152
	v_lshlrev_b64 v[152:153], 8, v[152:153]
	v_lshl_add_u64 v[152:153], v[6:7], 0, v[152:153]
	global_load_dword v152, v[152:153], off

; DI void prep_transpose(const float* W, int K, int Nsrc, int Nd, int kind, const float* kscale, bf16_t* dst, float* tileL, int L, int G) {
;     ...
;     const int tx = tid & 63, ty = tid >> 6;
;     const int src = colmap(kind, n0 + tx);
;     __syncthreads();
;     for (int kk = ty; kk < 64; kk += 8) {
;       float v = 0.f;
;       if (src >= 0) { v = W[(size_t)(k0 + kk) * Nsrc + src]; if (kscale) v *= kscale[k0 + kk]; }
;       tileL[kk * 65 + tx] = v;
;     }
.LBB0_124:
	v_mov_b32_e32 v40, 0
	v_mov_b32_e32 v56, 0
	v_mov_b32_e32 v72, 0
	v_mov_b32_e32 v88, 0
	v_mov_b32_e32 v104, 0
	v_mov_b32_e32 v120, 0
	v_mov_b32_e32 v136, 0
	v_mov_b32_e32 v152, 0
	s_and_saveexec_b64 s[2:3], s[0:1]
	s_cbranch_execz .Lmy_tp9_r
	v_add_u32_e32 v40, s22, v13
	v_ashrrev_i32_e32 v41, 31, v40
	v_lshlrev_b64 v[40:41], 8, v[40:41]
	v_lshl_add_u64 v[40:41], v[6:7], 0, v[40:41]
	global_load_dword v40, v[40:41], off
	v_add_u32_e32 v71, 8, v13
	v_add_u32_e32 v56, s22, v71
	v_ashrrev_i32_e32 v57, 31, v56
	v_lshlrev_b64 v[56:57], 8, v[56:57]
	v_lshl_add_u64 v[56:57], v[6:7], 0, v[56:57]
	global_load_dword v56, v[56:57], off
	v_add_u32_e32 v87, 16, v13
	v_add_u32_e32 v72, s22, v87
	v_ashrrev_i32_e32 v73, 31, v72
	v_lshlrev_b64 v[72:73], 8, v[72:73]
	v_lshl_add_u64 v[72:73], v[6:7], 0, v[72:73]
	global_load_dword v72, v[72:73], off
	v_add_u32_e32 v103, 24, v13
	v_add_u32_e32 v88, s22, v103
	v_ashrrev_i32_e32 v89, 31, v88
	v_lshlrev_b64 v[88:89], 8, v[88:89]
	v_lshl_add_u64 v[88:89], v[6:7], 0, v[88:89]
	global_load_dword v88, v[88:89], off
	v_add_u32_e32 v119, 32, v13
	v_add_u32_e32 v104, s22, v119
	v_ashrrev_i32_e32 v105, 31, v104
	v_lshlrev_b64 v[104:105], 8, v[104:105]
	v_lshl_add_u64 v[104:105], v[6:7], 0, v[104:105]
	global_load_dword v104, v[104:105], off
	v_add_u32_e32 v135, 40, v13
	v_add_u32_e32 v120, s22, v135
	v_ashrrev_i32_e32 v121, 31, v120
	v_lshlrev_b64 v[120:121], 8, v[120:121]
	v_lshl_add_u64 v[120:121], v[6:7], 0, v[120:121]
	global_load_dword v120, v[120:121], off
	v_add_u32_e32 v151, 48, v13
	v_add_u32_e32 v136, s22, v151
	v_ashrrev_i32_e32 v137, 31, v136
	v_lshlrev_b64 v[136:137], 8, v[136:137]
	v_lshl_add_u64 v[136:137], v[6:7], 0, v[136:137]
	global_load_dword v136, v[136:137], off
	v_add_u32_e32 v167, 56, v13
	v_add_u32_e32 v152, s22, v167
	v_ashrrev_i32_e32 v153, 31, v152
	v_lshlrev_b64 v[152:153], 8, v[152:153]
	v_lshl_add_u64 v[152:153], v[6:7], 0, v[152:153]
	global_load_dword v152, v[152:153], off

; DI void prep_transpose(const float* W, int K, int Nsrc, int Nd, int kind, const float* kscale, bf16_t* dst, float* tileL, int L, int G) {
;     ...
;     const int tx = tid & 63, ty = tid >> 6;
;     const int src = colmap(kind, n0 + tx);
;     __syncthreads();
;     for (int kk = ty; kk < 64; kk += 8) {
;       float v = 0.f;
;       if (src >= 0) { v = W[(size_t)(k0 + kk) * Nsrc + src]; if (kscale) v *= kscale[k0 + kk]; }
;       tileL[kk * 65 + tx] = v;
;     }
.LBB0_134:
	v_mov_b32_e32 v40, 0
	v_mov_b32_e32 v56, 0
	v_mov_b32_e32 v72, 0
	v_mov_b32_e32 v88, 0
	v_mov_b32_e32 v104, 0
	v_mov_b32_e32 v120, 0
	v_mov_b32_e32 v136, 0
	v_mov_b32_e32 v152, 0
	s_and_b64 vcc, exec, s[10:11]
	s_cbranch_vccnz .Lmy_tp10_w
	v_add_u32_e32 v40, s48, v13
	v_ashrrev_i32_e32 v41, 31, v40
	v_lshlrev_b64 v[40:41], 12, v[40:41]
	v_lshl_add_u64 v[40:41], v[6:7], 0, v[40:41]
	global_load_dword v40, v[40:41], off
	v_add_u32_e32 v71, 8, v13
	v_add_u32_e32 v56, s48, v71
	v_ashrrev_i32_e32 v57, 31, v56
	v_lshlrev_b64 v[56:57], 12, v[56:57]
	v_lshl_add_u64 v[56:57], v[6:7], 0, v[56:57]
	global_load_dword v56, v[56:57], off
	v_add_u32_e32 v87, 16, v13
	v_add_u32_e32 v72, s48, v87
	v_ashrrev_i32_e32 v73, 31, v72
	v_lshlrev_b64 v[72:73], 12, v[72:73]
	v_lshl_add_u64 v[72:73], v[6:7], 0, v[72:73]
	global_load_dword v72, v[72:73], off
	v_add_u32_e32 v103, 24, v13
	v_add_u32_e32 v88, s48, v103
	v_ashrrev_i32_e32 v89, 31, v88
	v_lshlrev_b64 v[88:89], 12, v[88:89]
	v_lshl_add_u64 v[88:89], v[6:7], 0, v[88:89]
	global_load_dword v88, v[88:89], off
	v_add_u32_e32 v119, 32, v13
	v_add_u32_e32 v104, s48, v119
	v_ashrrev_i32_e32 v105, 31, v104
	v_lshlrev_b64 v[104:105], 12, v[104:105]
	v_lshl_add_u64 v[104:105], v[6:7], 0, v[104:105]
	global_load_dword v104, v[104:105], off
	v_add_u32_e32 v135, 40, v13
	v_add_u32_e32 v120, s48, v135
	v_ashrrev_i32_e32 v121, 31, v120
	v_lshlrev_b64 v[120:121], 12, v[120:121]
	v_lshl_add_u64 v[120:121], v[6:7], 0, v[120:121]
	global_load_dword v120, v[120:121], off
	v_add_u32_e32 v151, 48, v13
	v_add_u32_e32 v136, s48, v151
	v_ashrrev_i32_e32 v137, 31, v136
	v_lshlrev_b64 v[136:137], 12, v[136:137]
	v_lshl_add_u64 v[136:137], v[6:7], 0, v[136:137]
	global_load_dword v136, v[136:137], off
	v_add_u32_e32 v167, 56, v13
	v_add_u32_e32 v152, s48, v167
	v_ashrrev_i32_e32 v153, 31, v152
	v_lshlrev_b64 v[152:153], 12, v[152:153]
	v_lshl_add_u64 v[152:153], v[6:7], 0, v[152:153]
	global_load_dword v152, v[152:153], off

; DI void prep_transpose(const float* W, int K, int Nsrc, int Nd, int kind, const float* kscale, bf16_t* dst, float* tileL, int L, int G) {
;     ...
;     const int tx = tid & 63, ty = tid >> 6;
;     const int src = colmap(kind, n0 + tx);
;     __syncthreads();
;     for (int kk = ty; kk < 64; kk += 8) {
;       float v = 0.f;
;       if (src >= 0) { v = W[(size_t)(k0 + kk) * Nsrc + src]; if (kscale) v *= kscale[k0 + kk]; }
;       tileL[kk * 65 + tx] = v;
;     }
.LBB0_142:
	v_mov_b32_e32 v48, 0
	v_mov_b32_e32 v64, 0
	v_mov_b32_e32 v80, 0
	v_mov_b32_e32 v96, 0
	v_mov_b32_e32 v112, 0
	v_mov_b32_e32 v128, 0
	v_mov_b32_e32 v144, 0
	v_mov_b32_e32 v160, 0
	s_and_b64 vcc, exec, s[10:11]
	s_cbranch_vccnz .Lmy_tp11_w
	v_add_u32_e32 v40, s50, v15
	v_ashrrev_i32_e32 v41, 31, v40
	v_lshlrev_b64 v[48:49], 12, v[40:41]
	v_lshl_add_u64 v[48:49], v[6:7], 0, v[48:49]
	global_load_dword v48, v[48:49], off
	v_add_u32_e32 v71, 8, v15
	v_add_u32_e32 v56, s50, v71
	v_ashrrev_i32_e32 v57, 31, v56
	v_lshlrev_b64 v[64:65], 12, v[56:57]
	v_lshl_add_u64 v[64:65], v[6:7], 0, v[64:65]
	global_load_dword v64, v[64:65], off
	v_add_u32_e32 v87, 16, v15
	v_add_u32_e32 v72, s50, v87
	v_ashrrev_i32_e32 v73, 31, v72
	v_lshlrev_b64 v[80:81], 12, v[72:73]
	v_lshl_add_u64 v[80:81], v[6:7], 0, v[80:81]
	global_load_dword v80, v[80:81], off
	v_add_u32_e32 v103, 24, v15
	v_add_u32_e32 v88, s50, v103
	v_ashrrev_i32_e32 v89, 31, v88
	v_lshlrev_b64 v[96:97], 12, v[88:89]
	v_lshl_add_u64 v[96:97], v[6:7], 0, v[96:97]
	global_load_dword v96, v[96:97], off
	v_add_u32_e32 v119, 32, v15
	v_add_u32_e32 v104, s50, v119
	v_ashrrev_i32_e32 v105, 31, v104
	v_lshlrev_b64 v[112:113], 12, v[104:105]
	v_lshl_add_u64 v[112:113], v[6:7], 0, v[112:113]
	global_load_dword v112, v[112:113], off
	v_add_u32_e32 v135, 40, v15
	v_add_u32_e32 v120, s50, v135
	v_ashrrev_i32_e32 v121, 31, v120
	v_lshlrev_b64 v[128:129], 12, v[120:121]
	v_lshl_add_u64 v[128:129], v[6:7], 0, v[128:129]
	global_load_dword v128, v[128:129], off
	v_add_u32_e32 v151, 48, v15
	v_add_u32_e32 v136, s50, v151
	v_ashrrev_i32_e32 v137, 31, v136
	v_lshlrev_b64 v[144:145], 12, v[136:137]
	v_lshl_add_u64 v[144:145], v[6:7], 0, v[144:145]
	global_load_dword v144, v[144:145], off
	v_add_u32_e32 v167, 56, v15
	v_add_u32_e32 v152, s50, v167
	v_ashrrev_i32_e32 v153, 31, v152
	v_lshlrev_b64 v[160:161], 12, v[152:153]
	v_lshl_add_u64 v[160:161], v[6:7], 0, v[160:161]
	global_load_dword v160, v[160:161], off
	s_and_b64 vcc, exec, s[2:3]
	s_cbranch_vccnz .Lmy_tp11_r
	v_lshl_add_u64 v[40:41], v[40:41], 2, s[38:39]
	global_load_dword v40, v[40:41], off
	v_lshl_add_u64 v[56:57], v[56:57], 2, s[38:39]
	global_load_dword v56, v[56:57], off
	v_lshl_add_u64 v[72:73], v[72:73], 2, s[38:39]
	global_load_dword v72, v[72:73], off
	v_lshl_add_u64 v[88:89], v[88:89], 2, s[38:39]
	global_load_dword v88, v[88:89], off
	v_lshl_add_u64 v[104:105], v[104:105], 2, s[38:39]
	global_load_dword v104, v[104:105], off
	v_lshl_add_u64 v[120:121], v[120:121], 2, s[38:39]
	global_load_dword v120, v[120:121], off
	v_lshl_add_u64 v[136:137], v[136:137], 2, s[38:39]
	global_load_dword v136, v[136:137], off
	v_lshl_add_u64 v[152:153], v[152:153], 2, s[38:39]
	global_load_dword v152, v[152:153], off
	s_waitcnt vmcnt(7)
	v_mul_f32_e32 v48, v48, v40
	s_waitcnt vmcnt(6)
	v_mul_f32_e32 v64, v64, v56
	s_waitcnt vmcnt(5)
	v_mul_f32_e32 v80, v80, v72
	s_waitcnt vmcnt(4)
	v_mul_f32_e32 v96, v96, v88
	s_waitcnt vmcnt(3)
	v_mul_f32_e32 v112, v112, v104
	s_waitcnt vmcnt(2)
	v_mul_f32_e32 v128, v128, v120
	s_waitcnt vmcnt(1)
	v_mul_f32_e32 v144, v144, v136
	s_waitcnt vmcnt(0)
	v_mul_f32_e32 v160, v160, v152
.Lmy_tp11_r:
.Lmy_tp11_w:
	s_waitcnt vmcnt(7)
	ds_write_b32 v2, v48
	s_waitcnt vmcnt(6)
	ds_write_b32 v2, v64 offset:2080
	s_waitcnt vmcnt(5)
	ds_write_b32 v2, v80 offset:4160
	s_waitcnt vmcnt(4)
	ds_write_b32 v2, v96 offset:6240
	s_waitcnt vmcnt(3)
	ds_write_b32 v2, v112 offset:8320
	s_waitcnt vmcnt(2)
	ds_write_b32 v2, v128 offset:10400
	s_waitcnt vmcnt(1)
	ds_write_b32 v2, v144 offset:12480
	s_waitcnt vmcnt(0)
	ds_write_b32 v2, v160 offset:14560
	s_branch .LBB0_138

; DI void prep_transpose(const float* W, int K, int Nsrc, int Nd, int kind, const float* kscale, bf16_t* dst, float* tileL, int L, int G) {
;     ...
;     const int tx = tid & 63, ty = tid >> 6;
;     const int src = colmap(kind, n0 + tx);
;     __syncthreads();
;     for (int kk = ty; kk < 64; kk += 8) {
;       float v = 0.f;
;       if (src >= 0) { v = W[(size_t)(k0 + kk) * Nsrc + src]; if (kscale) v *= kscale[k0 + kk]; }
;       tileL[kk * 65 + tx] = v;
;     }
.LBB0_151:
	v_mov_b32_e32 v40, 0
	v_mov_b32_e32 v56, 0
	v_mov_b32_e32 v72, 0
	v_mov_b32_e32 v88, 0
	v_mov_b32_e32 v104, 0
	v_mov_b32_e32 v120, 0
	v_mov_b32_e32 v136, 0
	v_mov_b32_e32 v152, 0
	s_andn2_b64 vcc, exec, s[38:39]
	s_cbranch_vccnz .Lmy_tp12_w
	v_add_u32_e32 v40, s46, v13
	v_ashrrev_i32_e32 v41, 31, v40
	v_lshlrev_b64 v[40:41], 12, v[40:41]
	v_lshl_add_u64 v[40:41], v[6:7], 0, v[40:41]
	global_load_dword v40, v[40:41], off
	v_add_u32_e32 v71, 8, v13
	v_add_u32_e32 v56, s46, v71
	v_ashrrev_i32_e32 v57, 31, v56
	v_lshlrev_b64 v[56:57], 12, v[56:57]
	v_lshl_add_u64 v[56:57], v[6:7], 0, v[56:57]
	global_load_dword v56, v[56:57], off
	v_add_u32_e32 v87, 16, v13
	v_add_u32_e32 v72, s46, v87
	v_ashrrev_i32_e32 v73, 31, v72
	v_lshlrev_b64 v[72:73], 12, v[72:73]
	v_lshl_add_u64 v[72:73], v[6:7], 0, v[72:73]
	global_load_dword v72, v[72:73], off
	v_add_u32_e32 v103, 24, v13
	v_add_u32_e32 v88, s46, v103
	v_ashrrev_i32_e32 v89, 31, v88
	v_lshlrev_b64 v[88:89], 12, v[88:89]
	v_lshl_add_u64 v[88:89], v[6:7], 0, v[88:89]
	global_load_dword v88, v[88:89], off
	v_add_u32_e32 v119, 32, v13
	v_add_u32_e32 v104, s46, v119
	v_ashrrev_i32_e32 v105, 31, v104
	v_lshlrev_b64 v[104:105], 12, v[104:105]
	v_lshl_add_u64 v[104:105], v[6:7], 0, v[104:105]
	global_load_dword v104, v[104:105], off
	v_add_u32_e32 v135, 40, v13
	v_add_u32_e32 v120, s46, v135
	v_ashrrev_i32_e32 v121, 31, v120
	v_lshlrev_b64 v[120:121], 12, v[120:121]
	v_lshl_add_u64 v[120:121], v[6:7], 0, v[120:121]
	global_load_dword v120, v[120:121], off
	v_add_u32_e32 v151, 48, v13
	v_add_u32_e32 v136, s46, v151
	v_ashrrev_i32_e32 v137, 31, v136
	v_lshlrev_b64 v[136:137], 12, v[136:137]
	v_lshl_add_u64 v[136:137], v[6:7], 0, v[136:137]
	global_load_dword v136, v[136:137], off
	v_add_u32_e32 v167, 56, v13
	v_add_u32_e32 v152, s46, v167
	v_ashrrev_i32_e32 v153, 31, v152
	v_lshlrev_b64 v[152:153], 12, v[152:153]
	v_lshl_add_u64 v[152:153], v[6:7], 0, v[152:153]
	global_load_dword v152, v[152:153], off
